# GEMM k-loops: split k-tile barrier - reads-done barrier right after group 2 (DMA for tile+2 starts), the DMA-landed wait and a second barrier only after 3 MFMAs of the last group
# baseline (speedup 1.0000x reference)
; #define MFMA(a, b, c) __builtin_amdgcn_mfma_f32_32x32x16_bf16((a), (b), (c), 0, 0, 0)
;     ...
;     auto compute2 = [&](int buf) {
;       const char* lb = L0 + buf * BUFB;
; #pragma unroll
;       for (int ks = 0; ks < 4; ++ks) {
;         const int c = ks * 2 + hh;
;         bf16x8 wf[2], xf[MI];
; #pragma unroll
;         for (int j = 0; j < 2; ++j) { const int r = wn * 64 + j * 32 + l32; wf[j] = *(const bf16x8*)(lb + 256 * 128 + r * 128 + ((c ^ ((r >> 1) & 7)) << 4)); }
; #pragma unroll
;         for (int i = 0; i < MI; ++i) { const int r = wm * (MI * 32) + i * 32 + l32; xf[i] = *(const bf16x8*)(lb + r * 128 + ((c ^ ((r >> 1) & 7)) << 4)); }
; #pragma unroll
;         for (int i = 0; i < MI; ++i) {
;           acc[i][0] = MFMA(wf[0], xf[i], acc[i][0]);
;           acc[i][1] = MFMA(wf[1], xf[i], acc[i][1]);
;         }
;       }
;     };
;     ...
;       for (int kt = 0; kt < nk; ++kt) {
;         const int buf = kt & 1;
;         if (kt + 1 < nk) issue(kt + 1, buf ^ 1);
;         else if (chain & 2) issue_at(nmt * 256, nnt * BN, 0, buf ^ 1);
;         compute2(buf);
;         asm volatile("s_waitcnt vmcnt(0)" ::: "memory");
;         __syncthreads();
;       }
.Lgemm_g1_798:
	v_add_u32_e32 v0, s14, v173
	v_add_u32_e32 v254, v0, v171
	v_add_u32_e32 v0, v0, v170
	s_waitcnt lgkmcnt(3)
	v_mfma_f32_32x32x16_bf16 v[114:129], v[224:227], v[232:235], v[114:129]
	ds_read_b128 v[200:203], v254 offset:32768
	v_mfma_f32_32x32x16_bf16 v[98:113], v[228:231], v[232:235], v[98:113]
	ds_read_b128 v[204:207], v254 offset:36864
	s_waitcnt lgkmcnt(4)
	v_mfma_f32_32x32x16_bf16 v[82:97], v[224:227], v[240:243], v[82:97]
	ds_read_b128 v[208:211], v0
	v_mfma_f32_32x32x16_bf16 v[66:81], v[228:231], v[240:243], v[66:81]
	ds_read_b128 v[212:215], v0 offset:4096
	s_waitcnt lgkmcnt(5)
	v_mfma_f32_32x32x16_bf16 v[50:65], v[224:227], v[244:247], v[50:65]
	ds_read_b128 v[216:219], v0 offset:8192
	v_mfma_f32_32x32x16_bf16 v[34:49], v[228:231], v[244:247], v[34:49]
	ds_read_b128 v[220:223], v0 offset:12288
	s_waitcnt lgkmcnt(6)
	v_mfma_f32_32x32x16_bf16 v[18:33], v[224:227], v[248:251], v[18:33]
	v_mfma_f32_32x32x16_bf16 v[2:17], v[228:231], v[248:251], v[2:17]
	v_add_u32_e32 v0, s14, v172
	v_add_u32_e32 v254, v0, v171
	v_add_u32_e32 v0, v0, v170
	s_waitcnt lgkmcnt(3)
	v_mfma_f32_32x32x16_bf16 v[114:129], v[200:203], v[208:211], v[114:129]
	ds_read_b128 v[224:227], v254 offset:32768
	v_mfma_f32_32x32x16_bf16 v[98:113], v[204:207], v[208:211], v[98:113]
	ds_read_b128 v[228:231], v254 offset:36864
	s_waitcnt lgkmcnt(4)
	v_mfma_f32_32x32x16_bf16 v[82:97], v[200:203], v[212:215], v[82:97]
	ds_read_b128 v[232:235], v0
	v_mfma_f32_32x32x16_bf16 v[66:81], v[204:207], v[212:215], v[66:81]
	ds_read_b128 v[240:243], v0 offset:4096
	s_waitcnt lgkmcnt(5)
	v_mfma_f32_32x32x16_bf16 v[50:65], v[200:203], v[216:219], v[50:65]
	ds_read_b128 v[244:247], v0 offset:8192
	v_mfma_f32_32x32x16_bf16 v[34:49], v[204:207], v[216:219], v[34:49]
	ds_read_b128 v[248:251], v0 offset:12288
	s_waitcnt lgkmcnt(6)
	v_mfma_f32_32x32x16_bf16 v[18:33], v[200:203], v[220:223], v[18:33]
	v_mfma_f32_32x32x16_bf16 v[2:17], v[204:207], v[220:223], v[2:17]
	s_waitcnt lgkmcnt(0)
	s_barrier
	s_cbranch_scc1 .Lgemm_exit_798
	s_and_b32 s14, s11, 0x10000
	s_xor_b32 s15, s14, 0x10000
	s_add_i32 s15, s15, 0
	s_add_i32 s14, s14, 0
	v_add_u32_e32 v0, s14, v175
	v_add_u32_e32 v254, v0, v171
	v_add_u32_e32 v0, v0, v170
	v_mfma_f32_32x32x16_bf16 v[114:129], v[224:227], v[232:235], v[114:129]
	s_add_i32 s64, s15, 0x8000
	s_add_i32 m0, s15, s60
	v_lshl_add_u64 v[176:177], v[152:153], 0, s[2:3]
	global_load_lds_dwordx4 v[176:177], off
	v_mfma_f32_32x32x16_bf16 v[98:113], v[228:231], v[232:235], v[98:113]
	s_add_i32 m0, s15, s61
	v_lshl_add_u64 v[176:177], v[150:151], 0, s[2:3]
	global_load_lds_dwordx4 v[176:177], off
	s_add_i32 m0, s15, s62
	v_mfma_f32_32x32x16_bf16 v[82:97], v[224:227], v[240:243], v[82:97]
	v_lshl_add_u64 v[176:177], v[148:149], 0, s[2:3]
	global_load_lds_dwordx4 v[176:177], off
	s_add_i32 m0, s15, s63
	v_lshl_add_u64 v[176:177], v[146:147], 0, s[2:3]
	s_waitcnt vmcnt(3)
	s_barrier
	ds_read_b128 v[200:203], v254 offset:32768
	ds_read_b128 v[204:207], v254 offset:36864
	ds_read_b128 v[208:211], v0
	ds_read_b128 v[212:215], v0 offset:4096
	ds_read_b128 v[216:219], v0 offset:8192
	ds_read_b128 v[220:223], v0 offset:12288
	v_mfma_f32_32x32x16_bf16 v[66:81], v[228:231], v[240:243], v[66:81]
	global_load_lds_dwordx4 v[176:177], off
	s_add_i32 m0, s64, s60
	v_lshl_add_u64 v[176:177], v[144:145], 0, s[2:3]
	global_load_lds_dwordx4 v[176:177], off
	v_mfma_f32_32x32x16_bf16 v[50:65], v[224:227], v[244:247], v[50:65]
	s_add_i32 m0, s64, s61
	v_lshl_add_u64 v[176:177], v[142:143], 0, s[2:3]
	global_load_lds_dwordx4 v[176:177], off
	s_add_i32 m0, s64, s62
	v_mfma_f32_32x32x16_bf16 v[34:49], v[228:231], v[244:247], v[34:49]
	v_lshl_add_u64 v[176:177], v[140:141], 0, s[2:3]
	global_load_lds_dwordx4 v[176:177], off
	s_add_i32 m0, s64, s63
	v_lshl_add_u64 v[176:177], v[138:139], 0, s[2:3]
	v_mfma_f32_32x32x16_bf16 v[18:33], v[224:227], v[248:251], v[18:33]
	global_load_lds_dwordx4 v[176:177], off
	v_mfma_f32_32x32x16_bf16 v[2:17], v[228:231], v[248:251], v[2:17]
	s_branch .Lgemm_rot_798
;     ...
;     auto issue_at = [&](int mm0, int nn0, int kt, int buf) {
;       char* lb = L0 + buf * BUFB;
; #pragma unroll
;       for (int i = 0; i < 4; ++i) {
;         const int seg = wv * 4 + i, row = seg * 8 + gl_row;
;         const int c = (lane & 7) ^ ((row >> 1) & 7);
;         const u16* ap = (kt < g.split) ? g.a0 + (size_t)(mm0 + row) * g.ld0 + kt * g.ks0 : g.a1 + (size_t)(mm0 + row) * g.ld1 + (kt - g.split) * 64;
;         __builtin_amdgcn_global_load_lds((const unsigned*)(ap + c * 8), (__attribute__((address_space(3))) unsigned*)(lb + seg * 1024 + lane * 16), 16, 0, 0);
;       }
; #pragma unroll
;       for (int i = 0; i < BN / 64; ++i) {
;         const int seg = wv * (BN / 64) + i, row = seg * 8 + gl_row;
;         const int c = (lane & 7) ^ ((row >> 1) & 7);
;         __builtin_amdgcn_global_load_lds((const unsigned*)(g.W + (size_t)(nn0 + row) * g.K + kt * 64 + c * 8),
;                                          (__attribute__((address_space(3))) unsigned*)(lb + 256 * 128 + seg * 1024 + lane * 16), 16, 0, 0);
;       }
;     };
; template <int MODE, int EPI, int BN>
; DI void gemm_phase(CP p, const GArgs& g, int NT, char* smem) {
;     ...
;   for (int e = j; e < total; e += nj) {
;     const int grp = e / (8 * NT);
;     const int rem = e - grp * 8 * NT;
;     const int e2 = e + nj;
;     const bool has_next = can_chain && e2 < total;
;     const int grp2 = e2 / (8 * NT), rem2 = e2 - grp2 * 8 * NT;
;     const int chain = can_chain ? ((first ? 0 : 1) | (has_next ? 2 : 0)) : 0;
;     gemm_tile<MODE, EPI, BN>(p, g, x + 8 * (grp * 8 + (rem & 7)), rem >> 3, smem, chain, x + 8 * (grp2 * 8 + (rem2 & 7)), rem2 >> 3);
;     first = false;
;   }
.Lgemm_exit_798:
	s_waitcnt vmcnt(0)
	s_barrier
	v_readlane_b32 s60, v255, 0
	v_readlane_b32 s61, v255, 1
	v_readlane_b32 s62, v255, 2
	v_readlane_b32 s63, v255, 3
	v_readlane_b32 s64, v255, 4
	s_setprio 0
	v_mfma_f32_32x32x16_bf16 v[114:129], v[224:227], v[232:235], v[114:129]
	v_mfma_f32_32x32x16_bf16 v[98:113], v[228:231], v[232:235], v[98:113]
	v_mfma_f32_32x32x16_bf16 v[82:97], v[224:227], v[240:243], v[82:97]
	v_mfma_f32_32x32x16_bf16 v[66:81], v[228:231], v[240:243], v[66:81]
	v_mfma_f32_32x32x16_bf16 v[50:65], v[224:227], v[244:247], v[50:65]
	v_mfma_f32_32x32x16_bf16 v[34:49], v[228:231], v[244:247], v[34:49]
	v_mfma_f32_32x32x16_bf16 v[18:33], v[224:227], v[248:251], v[18:33]
	v_mfma_f32_32x32x16_bf16 v[2:17], v[228:231], v[248:251], v[2:17]
	s_add_i32 s95, s95, s76
	s_cmpk_gt_u32 s95, 0x9f
	s_cselect_b64 s[92:93], -1, 0
	s_and_b64 vcc, exec, s[92:93]
	s_cbranch_vccnz .LBB0_801
	s_mul_hi_u32 s2, s95, 0xcccccccd
	s_lshr_b32 s3, s2, 6
	s_mulk_i32 s3, 0xffb0
	s_lshl_b32 s11, s95, 3
	s_add_i32 s3, s3, s95
	s_and_b32 s2, s2, 0xffffc0
	s_and_b32 s11, s11, 56
	s_or_b32 s2, s2, s11
	v_readlane_b32 s11, v252, 38
	s_lshl_b32 s3, s3, 5
	s_or_b32 s2, s2, s11
	s_and_b32 s3, s3, 0xffffff00
	s_lshl_b32 s2, s2, 8
	v_add_u32_e32 v148, s3, v161
	v_add_u32_e32 v138, s2, v157
	v_ashrrev_i32_e32 v149, 31, v148
	v_ashrrev_i32_e32 v139, 31, v138
	v_lshl_add_u64 v[176:177], s[68:69], 0, v[136:137]
	v_lshl_add_u64 v[136:137], s[70:71], 0, v[136:137]
	v_lshlrev_b64 v[148:149], 11, v[148:149]
	v_add3_u32 v0, 0, v168, v169
	v_add_u32_e32 v140, s2, v161
	v_add_u32_e32 v142, s2, v165
	v_add_u32_e32 v144, s2, v167
	v_lshlrev_b64 v[138:139], 11, v[138:139]
	v_lshl_add_u64 v[136:137], v[136:137], 0, v[148:149]
	v_lshl_add_u64 v[148:149], s[70:71], 0, v[134:135]
	v_lshl_add_u64 v[134:135], s[68:69], 0, v[134:135]
	v_readfirstlane_b32 s2, v0
	v_lshl_add_u64 v[134:135], v[134:135], 0, v[138:139]
	s_mov_b32 m0, s2
	v_ashrrev_i32_e32 v141, 31, v140
	global_load_lds_dwordx4 v[134:135], off
	v_add3_u32 v134, 0, v160, v169
	v_ashrrev_i32_e32 v143, 31, v142
	v_lshlrev_b64 v[140:141], 11, v[140:141]
	v_readfirstlane_b32 s2, v134
	v_add3_u32 v135, 0, v162, v169
	v_lshlrev_b64 v[142:143], 11, v[142:143]
	v_lshl_add_u64 v[202:203], s[70:71], 0, v[132:133]
	v_lshl_add_u64 v[132:133], s[68:69], 0, v[132:133]
	v_lshl_add_u64 v[140:141], v[176:177], 0, v[140:141]
	s_mov_b32 m0, s2
	v_readfirstlane_b32 s2, v135
	v_lshl_add_u64 v[132:133], v[132:133], 0, v[142:143]
	global_load_lds_dwordx4 v[140:141], off
	s_mov_b32 m0, s2
	v_ashrrev_i32_e32 v145, 31, v144
	v_add_u32_e32 v146, s3, v157
	global_load_lds_dwordx4 v[132:133], off
	v_add3_u32 v132, 0, v166, v169
	v_ashrrev_i32_e32 v147, 31, v146
	v_lshl_add_u64 v[200:201], s[68:69], 0, v[130:131]
	v_lshlrev_b64 v[144:145], 11, v[144:145]
	v_readfirstlane_b32 s2, v132
	v_add_u32_e32 v0, 0x8000, v0
	v_add_u32_e32 v150, s3, v165
	v_add_u32_e32 v152, s3, v167
	v_lshlrev_b64 v[146:147], 11, v[146:147]
	v_lshl_add_u64 v[144:145], v[200:201], 0, v[144:145]
	s_mov_b32 m0, s2
	v_readfirstlane_b32 s2, v0
	v_add_u32_e32 v0, 0x8000, v134
	v_ashrrev_i32_e32 v151, 31, v150
	v_ashrrev_i32_e32 v153, 31, v152
	v_lshl_add_u64 v[146:147], v[148:149], 0, v[146:147]
	global_load_lds_dwordx4 v[144:145], off
	s_mov_b32 m0, s2
	v_readfirstlane_b32 s2, v0
	v_add_u32_e32 v0, 0x8000, v135
	v_lshlrev_b64 v[150:151], 11, v[150:151]
	v_lshlrev_b64 v[152:153], 11, v[152:153]
	global_load_lds_dwordx4 v[146:147], off
	s_mov_b32 m0, s2
	v_readfirstlane_b32 s2, v0
	v_add_u32_e32 v0, 0x8000, v132
	v_lshl_add_u64 v[152:153], s[70:71], 0, v[152:153]
	v_lshl_add_u64 v[150:151], v[202:203], 0, v[150:151]
	global_load_lds_dwordx4 v[136:137], off
	s_mov_b32 m0, s2
	v_readfirstlane_b32 s2, v0
	global_load_lds_dwordx4 v[150:151], off
	v_lshl_add_u64 v[130:131], v[152:153], 0, v[130:131]
	s_mov_b32 m0, s2
	s_nop 0
	global_load_lds_dwordx4 v[130:131], off

; #define MFMA(a, b, c) __builtin_amdgcn_mfma_f32_32x32x16_bf16((a), (b), (c), 0, 0, 0)
;     ...
;     auto compute2 = [&](int buf) {
;       const char* lb = L0 + buf * BUFB;
; #pragma unroll
;       for (int ks = 0; ks < 4; ++ks) {
;         const int c = ks * 2 + hh;
;         bf16x8 wf[2], xf[MI];
; #pragma unroll
;         for (int j = 0; j < 2; ++j) { const int r = wn * 64 + j * 32 + l32; wf[j] = *(const bf16x8*)(lb + 256 * 128 + r * 128 + ((c ^ ((r >> 1) & 7)) << 4)); }
; #pragma unroll
;         for (int i = 0; i < MI; ++i) { const int r = wm * (MI * 32) + i * 32 + l32; xf[i] = *(const bf16x8*)(lb + r * 128 + ((c ^ ((r >> 1) & 7)) << 4)); }
; #pragma unroll
;         for (int i = 0; i < MI; ++i) {
;           acc[i][0] = MFMA(wf[0], xf[i], acc[i][0]);
;           acc[i][1] = MFMA(wf[1], xf[i], acc[i][1]);
;         }
;       }
;     };
;     ...
;       for (int kt = 0; kt < nk; ++kt) {
;         const int buf = kt & 1;
;         if (kt + 1 < nk) issue(kt + 1, buf ^ 1);
;         else if (chain & 2) issue_at(nmt * 256, nnt * BN, 0, buf ^ 1);
;         compute2(buf);
;         asm volatile("s_waitcnt vmcnt(0)" ::: "memory");
;         __syncthreads();
;       }
.Lgemm_g1_1274:
	v_add_u32_e32 v233, s59, v199
	v_add_u32_e32 v230, v233, v175
	v_add_u32_e32 v234, v233, v174
	s_waitcnt lgkmcnt(3)
	v_mfma_f32_32x32x16_bf16 v[114:129], v[240:243], v[248:251], v[114:129]
	ds_read_b128 v[202:205], v230 offset:32768
	v_mfma_f32_32x32x16_bf16 v[98:113], v[244:247], v[248:251], v[98:113]
	ds_read_b128 v[206:209], v230 offset:36864
	s_waitcnt lgkmcnt(4)
	v_mfma_f32_32x32x16_bf16 v[82:97], v[240:243], v[214:217], v[82:97]
	ds_read_b128 v[210:213], v234
	v_mfma_f32_32x32x16_bf16 v[66:81], v[244:247], v[214:217], v[66:81]
	ds_read_b128 v[214:217], v234 offset:4096
	s_waitcnt lgkmcnt(5)
	v_mfma_f32_32x32x16_bf16 v[50:65], v[240:243], v[218:221], v[50:65]
	v_mfma_f32_32x32x16_bf16 v[34:49], v[244:247], v[218:221], v[34:49]
	ds_read_b128 v[218:221], v234 offset:8192
	s_waitcnt lgkmcnt(5)
	v_mfma_f32_32x32x16_bf16 v[18:33], v[240:243], v[222:225], v[18:33]
	v_mfma_f32_32x32x16_bf16 v[2:17], v[244:247], v[222:225], v[2:17]
	ds_read_b128 v[222:225], v234 offset:12288
	v_add_u32_e32 v233, s59, v176
	v_add_u32_e32 v230, v233, v175
	v_add_u32_e32 v234, v233, v174
	s_waitcnt lgkmcnt(3)
	v_mfma_f32_32x32x16_bf16 v[114:129], v[202:205], v[210:213], v[114:129]
	ds_read_b128 v[240:243], v230 offset:32768
	v_mfma_f32_32x32x16_bf16 v[98:113], v[206:209], v[210:213], v[98:113]
	ds_read_b128 v[244:247], v230 offset:36864
	s_waitcnt lgkmcnt(4)
	v_mfma_f32_32x32x16_bf16 v[82:97], v[202:205], v[214:217], v[82:97]
	ds_read_b128 v[248:251], v234
	v_mfma_f32_32x32x16_bf16 v[66:81], v[206:209], v[214:217], v[66:81]
	ds_read_b128 v[214:217], v234 offset:4096
	s_waitcnt lgkmcnt(5)
	v_mfma_f32_32x32x16_bf16 v[50:65], v[202:205], v[218:221], v[50:65]
	v_mfma_f32_32x32x16_bf16 v[34:49], v[206:209], v[218:221], v[34:49]
	ds_read_b128 v[218:221], v234 offset:8192
	s_waitcnt lgkmcnt(5)
	v_mfma_f32_32x32x16_bf16 v[18:33], v[202:205], v[222:225], v[18:33]
	v_mfma_f32_32x32x16_bf16 v[2:17], v[206:209], v[222:225], v[2:17]
	ds_read_b128 v[222:225], v234 offset:12288
	s_waitcnt lgkmcnt(0)
	s_barrier
	s_cbranch_scc1 .Lgemm_exit_1274
	s_and_b32 s59, s56, 0x10000
	s_xor_b32 s60, s59, 0x10000
	s_add_i32 s57, s58, 1
	s_add_i32 s60, s60, 0
	s_cmp_lt_u32 s58, 21
	s_cselect_b64 vcc, -1, 0
	v_add_u32_e32 v233, s59, v201
	v_add_u32_e32 v230, v233, v175
	v_add_u32_e32 v234, v233, v174
	v_mfma_f32_32x32x16_bf16 v[114:129], v[240:243], v[248:251], v[114:129]
	s_add_i32 s66, s60, 0x8000
	v_lshl_add_u64 v[226:227], v[160:161], 0, s[2:3]
	v_lshl_add_u64 v[228:229], v[144:145], 0, s[2:3]
	v_cndmask_b32_e32 v227, v229, v227, vcc
	v_cndmask_b32_e32 v226, v228, v226, vcc
	v_lshl_add_u64 v[226:227], v[0:1], 1, v[226:227]
	v_mfma_f32_32x32x16_bf16 v[98:113], v[244:247], v[248:251], v[98:113]
	s_add_i32 m0, s60, s62
	v_lshl_add_u64 v[228:229], v[142:143], 0, s[2:3]
	global_load_lds_dwordx4 v[226:227], off
	v_lshl_add_u64 v[226:227], v[158:159], 0, s[2:3]
	v_cndmask_b32_e32 v227, v229, v227, vcc
	v_cndmask_b32_e32 v226, v228, v226, vcc
	v_mfma_f32_32x32x16_bf16 v[82:97], v[240:243], v[214:217], v[82:97]
	v_lshl_add_u64 v[226:227], v[130:131], 1, v[226:227]
	s_add_i32 m0, s60, s63
	v_lshl_add_u64 v[228:229], v[140:141], 0, s[2:3]
	global_load_lds_dwordx4 v[226:227], off
	v_lshl_add_u64 v[226:227], v[156:157], 0, s[2:3]
	v_cndmask_b32_e32 v227, v229, v227, vcc
	s_waitcnt vmcnt(2)
	s_barrier
	ds_read_b128 v[202:205], v230 offset:32768
	ds_read_b128 v[206:209], v230 offset:36864
	ds_read_b128 v[210:213], v234
	v_mfma_f32_32x32x16_bf16 v[66:81], v[244:247], v[214:217], v[66:81]
	ds_read_b128 v[214:217], v234 offset:4096
	v_cndmask_b32_e32 v226, v228, v226, vcc
	v_lshl_add_u64 v[226:227], v[132:133], 1, v[226:227]
	s_add_i32 m0, s60, s64
	v_lshl_add_u64 v[228:229], v[138:139], 0, s[2:3]
	global_load_lds_dwordx4 v[226:227], off
	v_lshl_add_u64 v[226:227], v[154:155], 0, s[2:3]
	v_mfma_f32_32x32x16_bf16 v[50:65], v[240:243], v[218:221], v[50:65]
	v_cndmask_b32_e32 v226, v228, v226, vcc
	v_cndmask_b32_e32 v227, v229, v227, vcc
	s_add_i32 m0, s60, s65
	v_lshl_add_u64 v[226:227], v[134:135], 1, v[226:227]
	global_load_lds_dwordx4 v[226:227], off
	s_add_i32 m0, s66, s62
	v_mfma_f32_32x32x16_bf16 v[34:49], v[244:247], v[218:221], v[34:49]
	ds_read_b128 v[218:221], v234 offset:8192
	v_lshl_add_u64 v[226:227], v[146:147], 0, s[2:3]
	global_load_lds_dwordx4 v[226:227], off
	s_add_i32 m0, s66, s63
	v_lshl_add_u64 v[226:227], v[148:149], 0, s[2:3]
	global_load_lds_dwordx4 v[226:227], off
	s_add_i32 m0, s66, s64
	v_mfma_f32_32x32x16_bf16 v[18:33], v[240:243], v[222:225], v[18:33]
	v_lshl_add_u64 v[226:227], v[150:151], 0, s[2:3]
	global_load_lds_dwordx4 v[226:227], off
	v_lshl_add_u64 v[226:227], v[152:153], 0, s[2:3]
	s_add_i32 m0, s66, s65
	s_add_i32 s58, s59, 0
	global_load_lds_dwordx4 v[226:227], off
	v_mfma_f32_32x32x16_bf16 v[2:17], v[244:247], v[222:225], v[2:17]
	ds_read_b128 v[222:225], v234 offset:12288
	s_branch .Lgemm_rot_1274
;     ...
;     auto issue_at = [&](int mm0, int nn0, int kt, int buf) {
;       char* lb = L0 + buf * BUFB;
; #pragma unroll
;       for (int i = 0; i < 4; ++i) {
;         const int seg = wv * 4 + i, row = seg * 8 + gl_row;
;         const int c = (lane & 7) ^ ((row >> 1) & 7);
;         const u16* ap = (kt < g.split) ? g.a0 + (size_t)(mm0 + row) * g.ld0 + kt * g.ks0 : g.a1 + (size_t)(mm0 + row) * g.ld1 + (kt - g.split) * 64;
;         __builtin_amdgcn_global_load_lds((const unsigned*)(ap + c * 8), (__attribute__((address_space(3))) unsigned*)(lb + seg * 1024 + lane * 16), 16, 0, 0);
;       }
; #pragma unroll
;       for (int i = 0; i < BN / 64; ++i) {
;         const int seg = wv * (BN / 64) + i, row = seg * 8 + gl_row;
;         const int c = (lane & 7) ^ ((row >> 1) & 7);
;         __builtin_amdgcn_global_load_lds((const unsigned*)(g.W + (size_t)(nn0 + row) * g.K + kt * 64 + c * 8),
;                                          (__attribute__((address_space(3))) unsigned*)(lb + 256 * 128 + seg * 1024 + lane * 16), 16, 0, 0);
;       }
;     };
; template <int MODE, int EPI, int BN>
; DI void gemm_phase(CP p, const GArgs& g, int NT, char* smem) {
;     ...
;   for (int e = j; e < total; e += nj) {
;     const int grp = e / (8 * NT);
;     const int rem = e - grp * 8 * NT;
;     const int e2 = e + nj;
;     const bool has_next = can_chain && e2 < total;
;     const int grp2 = e2 / (8 * NT), rem2 = e2 - grp2 * 8 * NT;
;     const int chain = can_chain ? ((first ? 0 : 1) | (has_next ? 2 : 0)) : 0;
;     gemm_tile<MODE, EPI, BN>(p, g, x + 8 * (grp * 8 + (rem & 7)), rem >> 3, smem, chain, x + 8 * (grp2 * 8 + (rem2 & 7)), rem2 >> 3);
;     first = false;
;   }
.Lgemm_exit_1274:
	s_waitcnt vmcnt(0)
	s_barrier
	v_readlane_b32 s62, v255, 0
	v_readlane_b32 s63, v255, 1
	v_readlane_b32 s64, v255, 2
	v_readlane_b32 s65, v255, 3
	v_readlane_b32 s66, v255, 4
	s_setprio 0
	v_mfma_f32_32x32x16_bf16 v[114:129], v[240:243], v[248:251], v[114:129]
	v_mfma_f32_32x32x16_bf16 v[98:113], v[244:247], v[248:251], v[98:113]
	v_mfma_f32_32x32x16_bf16 v[82:97], v[240:243], v[214:217], v[82:97]
	v_mfma_f32_32x32x16_bf16 v[66:81], v[244:247], v[214:217], v[66:81]
	v_mfma_f32_32x32x16_bf16 v[50:65], v[240:243], v[218:221], v[50:65]
	v_mfma_f32_32x32x16_bf16 v[34:49], v[244:247], v[218:221], v[34:49]
	v_mfma_f32_32x32x16_bf16 v[18:33], v[240:243], v[222:225], v[18:33]
	v_mfma_f32_32x32x16_bf16 v[2:17], v[244:247], v[222:225], v[2:17]
	s_add_i32 s15, s15, s10
	s_cmp_gt_u32 s15, 63
	s_cselect_b64 s[58:59], -1, 0
	s_and_b64 vcc, exec, s[58:59]
	s_cbranch_vccnz .LBB0_1277
	s_lshr_b32 s2, s15, 2
	s_and_b32 s2, s2, 0xffffff8
	s_and_b32 s3, s15, 7
	s_or_b32 s3, s2, s3
	s_lshl_b32 s2, s2, 7
	s_lshl_b32 s56, s15, 5
	s_sub_i32 s2, s56, s2
	s_lshl_b32 s3, s3, 11
	s_and_b32 s2, s2, 0xffffff00
	s_or_b32 s3, s3, s71
	v_add_u32_e32 v144, s2, v173
	v_lshlrev_b64 v[130:131], 1, v[130:131]
	v_mov_b64_e32 v[142:143], s[46:47]
	v_lshlrev_b64 v[132:133], 1, v[132:133]
	v_add_u32_e32 v0, s3, v163
	v_add_u32_e32 v148, s3, v168
	v_add_u32_e32 v149, s3, v171
	v_add_u32_e32 v150, s3, v173
	v_add_u32_e32 v151, s2, v163
	v_add_u32_e32 v146, s2, v168
	v_add_u32_e32 v147, s2, v171
	v_lshl_add_u64 v[138:139], s[42:43], 0, v[130:131]
	v_lshlrev_b64 v[134:135], 1, v[134:135]
	v_lshl_add_u64 v[130:131], s[46:47], 0, v[130:131]
	v_mad_i64_i32 v[142:143], s[2:3], v144, s96, v[142:143]
	v_lshl_add_u64 v[144:145], s[46:47], 0, v[132:133]
	v_lshl_add_u64 v[140:141], s[42:43], 0, v[134:135]
	v_mad_i64_i32 v[144:145], s[2:3], v147, s96, v[144:145]
	v_mad_i64_i32 v[130:131], s[2:3], v146, s96, v[130:131]
	v_lshl_add_u64 v[146:147], s[46:47], 0, v[136:137]
	v_lshl_add_u64 v[132:133], s[42:43], 0, v[132:133]
	v_lshl_add_u64 v[136:137], s[42:43], 0, v[136:137]
	v_mad_i64_i32 v[146:147], s[2:3], v151, s96, v[146:147]
	v_mad_i64_i32 v[140:141], s[2:3], v150, s29, v[140:141]
	v_mad_i64_i32 v[132:133], s[2:3], v149, s29, v[132:133]
	v_mad_i64_i32 v[138:139], s[2:3], v148, s29, v[138:139]
	v_mad_i64_i32 v[136:137], s[2:3], v0, s29, v[136:137]
	v_add3_u32 v0, 0, v177, v178
	s_nop 0
	v_readfirstlane_b32 s2, v0
	s_mov_b32 m0, s2
	v_add_u32_e32 v0, 0x8000, v0
	global_load_lds_dwordx4 v[136:137], off
	v_add3_u32 v136, 0, v169, v178
	v_add3_u32 v137, 0, v170, v178
	v_readfirstlane_b32 s2, v136
	s_mov_b32 m0, s2
	v_readfirstlane_b32 s2, v137
	global_load_lds_dwordx4 v[138:139], off
	s_mov_b32 m0, s2
	s_nop 0
	global_load_lds_dwordx4 v[132:133], off
	v_add3_u32 v132, 0, v172, v178
	s_nop 0
	v_readfirstlane_b32 s2, v132
	s_mov_b32 m0, s2
	v_readfirstlane_b32 s2, v0
	v_add_u32_e32 v0, 0x8000, v136
	global_load_lds_dwordx4 v[140:141], off
	s_mov_b32 m0, s2
	v_readfirstlane_b32 s2, v0
	v_add_u32_e32 v0, 0x8000, v137
	global_load_lds_dwordx4 v[146:147], off
	s_mov_b32 m0, s2
	v_readfirstlane_b32 s2, v0
	v_add_u32_e32 v0, 0x8000, v132
	global_load_lds_dwordx4 v[130:131], off
	s_mov_b32 m0, s2
	v_readfirstlane_b32 s2, v0
	global_load_lds_dwordx4 v[144:145], off
	v_lshl_add_u64 v[130:131], v[142:143], 0, v[134:135]
	s_mov_b32 m0, s2
	s_nop 0
	global_load_lds_dwordx4 v[130:131], off

; #define MFMA(a, b, c) __builtin_amdgcn_mfma_f32_32x32x16_bf16((a), (b), (c), 0, 0, 0)
;     ...
;     auto compute2 = [&](int buf) {
;       const char* lb = L0 + buf * BUFB;
; #pragma unroll
;       for (int ks = 0; ks < 4; ++ks) {
;         const int c = ks * 2 + hh;
;         bf16x8 wf[2], xf[MI];
; #pragma unroll
;         for (int j = 0; j < 2; ++j) { const int r = wn * 64 + j * 32 + l32; wf[j] = *(const bf16x8*)(lb + 256 * 128 + r * 128 + ((c ^ ((r >> 1) & 7)) << 4)); }
; #pragma unroll
;         for (int i = 0; i < MI; ++i) { const int r = wm * (MI * 32) + i * 32 + l32; xf[i] = *(const bf16x8*)(lb + r * 128 + ((c ^ ((r >> 1) & 7)) << 4)); }
; #pragma unroll
;         for (int i = 0; i < MI; ++i) {
;           acc[i][0] = MFMA(wf[0], xf[i], acc[i][0]);
;           acc[i][1] = MFMA(wf[1], xf[i], acc[i][1]);
;         }
;       }
;     };
;     ...
;       for (int kt = 0; kt < nk; ++kt) {
;         const int buf = kt & 1;
;         if (kt + 1 < nk) issue(kt + 1, buf ^ 1);
;         else if (chain & 2) issue_at(nmt * 256, nnt * BN, 0, buf ^ 1);
;         compute2(buf);
;         asm volatile("s_waitcnt vmcnt(0)" ::: "memory");
;         __syncthreads();
;       }
.Lgemm_g1_1371:
	v_add_u32_e32 v0, s17, v172
	v_add_u32_e32 v175, v0, v170
	v_add_u32_e32 v0, v0, v169
	s_waitcnt lgkmcnt(3)
	v_mfma_f32_32x32x16_bf16 v[114:129], v[224:227], v[232:235], v[114:129]
	ds_read_b128 v[200:203], v175 offset:32768
	v_mfma_f32_32x32x16_bf16 v[98:113], v[228:231], v[232:235], v[98:113]
	ds_read_b128 v[204:207], v175 offset:36864
	s_waitcnt lgkmcnt(4)
	v_mfma_f32_32x32x16_bf16 v[82:97], v[224:227], v[240:243], v[82:97]
	ds_read_b128 v[208:211], v0
	v_mfma_f32_32x32x16_bf16 v[66:81], v[228:231], v[240:243], v[66:81]
	ds_read_b128 v[212:215], v0 offset:4096
	s_waitcnt lgkmcnt(5)
	v_mfma_f32_32x32x16_bf16 v[50:65], v[224:227], v[244:247], v[50:65]
	ds_read_b128 v[216:219], v0 offset:8192
	v_mfma_f32_32x32x16_bf16 v[34:49], v[228:231], v[244:247], v[34:49]
	ds_read_b128 v[220:223], v0 offset:12288
	s_waitcnt lgkmcnt(6)
	v_mfma_f32_32x32x16_bf16 v[18:33], v[224:227], v[248:251], v[18:33]
	v_mfma_f32_32x32x16_bf16 v[2:17], v[228:231], v[248:251], v[2:17]
	v_add_u32_e32 v0, s17, v171
	v_add_u32_e32 v175, v0, v170
	v_add_u32_e32 v0, v0, v169
	s_waitcnt lgkmcnt(3)
	v_mfma_f32_32x32x16_bf16 v[114:129], v[200:203], v[208:211], v[114:129]
	ds_read_b128 v[224:227], v175 offset:32768
	v_mfma_f32_32x32x16_bf16 v[98:113], v[204:207], v[208:211], v[98:113]
	ds_read_b128 v[228:231], v175 offset:36864
	s_waitcnt lgkmcnt(4)
	v_mfma_f32_32x32x16_bf16 v[82:97], v[200:203], v[212:215], v[82:97]
	ds_read_b128 v[232:235], v0
	v_mfma_f32_32x32x16_bf16 v[66:81], v[204:207], v[212:215], v[66:81]
	ds_read_b128 v[240:243], v0 offset:4096
	s_waitcnt lgkmcnt(5)
	v_mfma_f32_32x32x16_bf16 v[50:65], v[200:203], v[216:219], v[50:65]
	ds_read_b128 v[244:247], v0 offset:8192
	v_mfma_f32_32x32x16_bf16 v[34:49], v[204:207], v[216:219], v[34:49]
	ds_read_b128 v[248:251], v0 offset:12288
	s_waitcnt lgkmcnt(6)
	v_mfma_f32_32x32x16_bf16 v[18:33], v[200:203], v[220:223], v[18:33]
	v_mfma_f32_32x32x16_bf16 v[2:17], v[204:207], v[220:223], v[2:17]
	s_waitcnt lgkmcnt(0)
	s_barrier
	s_cbranch_scc1 .Lgemm_exit_1371
	s_and_b32 s17, s16, 0x10000
	s_xor_b32 s43, s17, 0x10000
	s_add_i32 s43, s43, 0
	s_add_i32 s17, s17, 0
	v_add_u32_e32 v0, s17, v174
	v_add_u32_e32 v175, v0, v170
	v_add_u32_e32 v0, v0, v169
	v_mfma_f32_32x32x16_bf16 v[114:129], v[224:227], v[232:235], v[114:129]
	s_add_i32 s64, s43, 0x8000
	s_add_i32 m0, s43, s60
	v_lshl_add_u64 v[176:177], v[152:153], 0, s[10:11]
	global_load_lds_dwordx4 v[176:177], off
	v_mfma_f32_32x32x16_bf16 v[98:113], v[228:231], v[232:235], v[98:113]
	s_add_i32 m0, s43, s61
	v_lshl_add_u64 v[176:177], v[150:151], 0, s[10:11]
	global_load_lds_dwordx4 v[176:177], off
	s_add_i32 m0, s43, s62
	v_mfma_f32_32x32x16_bf16 v[82:97], v[224:227], v[240:243], v[82:97]
	v_lshl_add_u64 v[176:177], v[148:149], 0, s[10:11]
	global_load_lds_dwordx4 v[176:177], off
	s_add_i32 m0, s43, s63
	v_lshl_add_u64 v[176:177], v[146:147], 0, s[10:11]
	s_waitcnt vmcnt(3)
	s_barrier
	ds_read_b128 v[200:203], v175 offset:32768
	ds_read_b128 v[204:207], v175 offset:36864
	ds_read_b128 v[208:211], v0
	ds_read_b128 v[212:215], v0 offset:4096
	ds_read_b128 v[216:219], v0 offset:8192
	ds_read_b128 v[220:223], v0 offset:12288
	v_mfma_f32_32x32x16_bf16 v[66:81], v[228:231], v[240:243], v[66:81]
	global_load_lds_dwordx4 v[176:177], off
	s_add_i32 m0, s64, s60
	v_lshl_add_u64 v[176:177], v[144:145], 0, s[10:11]
	global_load_lds_dwordx4 v[176:177], off
	v_mfma_f32_32x32x16_bf16 v[50:65], v[224:227], v[244:247], v[50:65]
	s_add_i32 m0, s64, s61
	v_lshl_add_u64 v[176:177], v[142:143], 0, s[10:11]
	global_load_lds_dwordx4 v[176:177], off
	s_add_i32 m0, s64, s62
	v_mfma_f32_32x32x16_bf16 v[34:49], v[228:231], v[244:247], v[34:49]
	v_lshl_add_u64 v[176:177], v[140:141], 0, s[10:11]
	global_load_lds_dwordx4 v[176:177], off
	s_add_i32 m0, s64, s63
	v_lshl_add_u64 v[176:177], v[138:139], 0, s[10:11]
	v_mfma_f32_32x32x16_bf16 v[18:33], v[224:227], v[248:251], v[18:33]
	global_load_lds_dwordx4 v[176:177], off
	v_mfma_f32_32x32x16_bf16 v[2:17], v[228:231], v[248:251], v[2:17]
	s_branch .Lgemm_rot_1371
;     ...
;     auto issue_at = [&](int mm0, int nn0, int kt, int buf) {
;       char* lb = L0 + buf * BUFB;
; #pragma unroll
;       for (int i = 0; i < 4; ++i) {
;         const int seg = wv * 4 + i, row = seg * 8 + gl_row;
;         const int c = (lane & 7) ^ ((row >> 1) & 7);
;         const u16* ap = (kt < g.split) ? g.a0 + (size_t)(mm0 + row) * g.ld0 + kt * g.ks0 : g.a1 + (size_t)(mm0 + row) * g.ld1 + (kt - g.split) * 64;
;         __builtin_amdgcn_global_load_lds((const unsigned*)(ap + c * 8), (__attribute__((address_space(3))) unsigned*)(lb + seg * 1024 + lane * 16), 16, 0, 0);
;       }
; #pragma unroll
;       for (int i = 0; i < BN / 64; ++i) {
;         const int seg = wv * (BN / 64) + i, row = seg * 8 + gl_row;
;         const int c = (lane & 7) ^ ((row >> 1) & 7);
;         __builtin_amdgcn_global_load_lds((const unsigned*)(g.W + (size_t)(nn0 + row) * g.K + kt * 64 + c * 8),
;                                          (__attribute__((address_space(3))) unsigned*)(lb + 256 * 128 + seg * 1024 + lane * 16), 16, 0, 0);
;       }
;     };
; template <int MODE, int EPI, int BN>
; DI void gemm_phase(CP p, const GArgs& g, int NT, char* smem) {
;     ...
;   for (int e = j; e < total; e += nj) {
;     const int grp = e / (8 * NT);
;     const int rem = e - grp * 8 * NT;
;     const int e2 = e + nj;
;     const bool has_next = can_chain && e2 < total;
;     const int grp2 = e2 / (8 * NT), rem2 = e2 - grp2 * 8 * NT;
;     const int chain = can_chain ? ((first ? 0 : 1) | (has_next ? 2 : 0)) : 0;
;     gemm_tile<MODE, EPI, BN>(p, g, x + 8 * (grp * 8 + (rem & 7)), rem >> 3, smem, chain, x + 8 * (grp2 * 8 + (rem2 & 7)), rem2 >> 3);
;     first = false;
;   }
.Lgemm_exit_1371:
	s_waitcnt vmcnt(0)
	s_barrier
	v_readlane_b32 s60, v255, 0
	v_readlane_b32 s61, v255, 1
	v_readlane_b32 s62, v255, 2
	v_readlane_b32 s63, v255, 3
	v_readlane_b32 s64, v255, 4
	s_setprio 0
	v_mfma_f32_32x32x16_bf16 v[114:129], v[224:227], v[232:235], v[114:129]
	v_mfma_f32_32x32x16_bf16 v[98:113], v[228:231], v[232:235], v[98:113]
	v_mfma_f32_32x32x16_bf16 v[82:97], v[224:227], v[240:243], v[82:97]
	v_mfma_f32_32x32x16_bf16 v[66:81], v[228:231], v[240:243], v[66:81]
	v_mfma_f32_32x32x16_bf16 v[50:65], v[224:227], v[244:247], v[50:65]
	v_mfma_f32_32x32x16_bf16 v[34:49], v[228:231], v[244:247], v[34:49]
	v_mfma_f32_32x32x16_bf16 v[18:33], v[224:227], v[248:251], v[18:33]
	v_mfma_f32_32x32x16_bf16 v[2:17], v[228:231], v[248:251], v[2:17]
	s_add_i32 s51, s51, s50
	s_cmpk_gt_u32 s51, 0x15f
	s_cselect_b64 s[10:11], -1, 0
	s_and_b64 vcc, exec, s[10:11]
	s_cbranch_vccnz .LBB0_1374
	s_mul_hi_u32 s16, s51, 0xba2e8ba3
	s_lshr_b32 s16, s16, 7
	s_mul_i32 s17, s16, 0xffffff50
	s_lshl_b32 s43, s51, 3
	s_add_i32 s17, s17, s51
	s_lshl_b32 s16, s16, 6
	s_and_b32 s43, s43, 56
	s_or_b32 s16, s16, s43
	s_lshl_b32 s17, s17, 5
	s_or_b32 s16, s16, s72
	s_and_b32 s17, s17, 0xffffff00
	s_lshl_b32 s16, s16, 8
	v_add_u32_e32 v148, s17, v158
	v_add_u32_e32 v138, s16, v156
	v_ashrrev_i32_e32 v149, 31, v148
	v_ashrrev_i32_e32 v139, 31, v138
	v_lshl_add_u64 v[176:177], s[46:47], 0, v[136:137]
	v_lshl_add_u64 v[136:137], s[48:49], 0, v[136:137]
	v_lshlrev_b64 v[148:149], 11, v[148:149]
	v_add3_u32 v0, 0, v167, v168
	v_add_u32_e32 v140, s16, v158
	v_add_u32_e32 v142, s16, v164
	v_add_u32_e32 v144, s16, v166
	v_lshlrev_b64 v[138:139], 11, v[138:139]
	v_lshl_add_u64 v[136:137], v[136:137], 0, v[148:149]
	v_lshl_add_u64 v[148:149], s[48:49], 0, v[134:135]
	v_lshl_add_u64 v[134:135], s[46:47], 0, v[134:135]
	v_readfirstlane_b32 s16, v0
	v_lshl_add_u64 v[134:135], v[134:135], 0, v[138:139]
	s_mov_b32 m0, s16
	v_ashrrev_i32_e32 v141, 31, v140
	global_load_lds_dwordx4 v[134:135], off
	v_add3_u32 v134, 0, v157, v168
	v_ashrrev_i32_e32 v143, 31, v142
	v_lshlrev_b64 v[140:141], 11, v[140:141]
	v_readfirstlane_b32 s16, v134
	v_add3_u32 v135, 0, v159, v168
	v_lshlrev_b64 v[142:143], 11, v[142:143]
	v_lshl_add_u64 v[202:203], s[48:49], 0, v[132:133]
	v_lshl_add_u64 v[132:133], s[46:47], 0, v[132:133]
	v_lshl_add_u64 v[140:141], v[176:177], 0, v[140:141]
	s_mov_b32 m0, s16
	v_readfirstlane_b32 s16, v135
	v_lshl_add_u64 v[132:133], v[132:133], 0, v[142:143]
	global_load_lds_dwordx4 v[140:141], off
	s_mov_b32 m0, s16
	v_ashrrev_i32_e32 v145, 31, v144
	v_add_u32_e32 v146, s17, v156
	global_load_lds_dwordx4 v[132:133], off
	v_add3_u32 v132, 0, v165, v168
	v_ashrrev_i32_e32 v147, 31, v146
	v_lshl_add_u64 v[200:201], s[46:47], 0, v[130:131]
	v_lshlrev_b64 v[144:145], 11, v[144:145]
	v_readfirstlane_b32 s16, v132
	v_add_u32_e32 v0, 0x8000, v0
	v_add_u32_e32 v150, s17, v164
	v_add_u32_e32 v152, s17, v166
	v_lshlrev_b64 v[146:147], 11, v[146:147]
	v_lshl_add_u64 v[144:145], v[200:201], 0, v[144:145]
	s_mov_b32 m0, s16
	v_readfirstlane_b32 s16, v0
	v_add_u32_e32 v0, 0x8000, v134
	v_ashrrev_i32_e32 v151, 31, v150
	v_ashrrev_i32_e32 v153, 31, v152
	v_lshl_add_u64 v[146:147], v[148:149], 0, v[146:147]
	global_load_lds_dwordx4 v[144:145], off
	s_mov_b32 m0, s16
	v_readfirstlane_b32 s16, v0
	v_add_u32_e32 v0, 0x8000, v135
	v_lshlrev_b64 v[150:151], 11, v[150:151]
	v_lshlrev_b64 v[152:153], 11, v[152:153]
	global_load_lds_dwordx4 v[146:147], off
	s_mov_b32 m0, s16
	v_readfirstlane_b32 s16, v0
	v_add_u32_e32 v0, 0x8000, v132
	v_lshl_add_u64 v[152:153], s[48:49], 0, v[152:153]
	v_lshl_add_u64 v[150:151], v[202:203], 0, v[150:151]
	global_load_lds_dwordx4 v[136:137], off
	s_mov_b32 m0, s16
	v_readfirstlane_b32 s16, v0
	global_load_lds_dwordx4 v[150:151], off
	v_lshl_add_u64 v[130:131], v[152:153], 0, v[130:131]
	s_mov_b32 m0, s16
	s_nop 0
	global_load_lds_dwordx4 v[130:131], off
